# grid barrier: waiting workgroups poll the cross-XCD release generation directly instead of the per-XCD word their leader republishes (one relay hop less); otherwise as v42
# speedup vs baseline: 1.0024x; 1.0024x over previous
; __device__ __forceinline__ unsigned xb_ld(unsigned* p)              { return __hip_atomic_load(p, __ATOMIC_RELAXED, __HIP_MEMORY_SCOPE_AGENT); }
; __device__ __forceinline__ unsigned xb_add(unsigned* p, unsigned v) { return __hip_atomic_fetch_add(p, v, __ATOMIC_RELAXED, __HIP_MEMORY_SCOPE_AGENT); }
; #define XB_SPIN(cond, bar) do { unsigned _sp = 0; while (cond) { __builtin_amdgcn_s_sleep(1); \
;     if ((++_sp & 255u) == 0u) { if (xb_ld(&(bar)[XB_TMO])) break; if (_sp > XB_SPIN_CAP) { atomicAdd(&(bar)[XB_TMO], 1u); break; } } } } while (0)
; __device__ __forceinline__ void xcd_barrier(const XcdBarrier& b) {
;     ...
;         const unsigned old = xb_add(&bar[XB_XSUB(b.x)], 1u);
;         const unsigned gen = old / nloc;
;         if (old + 1u == (gen + 1u) * nloc) {
;             __builtin_amdgcn_fence(__ATOMIC_RELEASE, "agent");
;             asm volatile("s_waitcnt vmcnt(0)" ::: "memory");
;             const unsigned og = xb_add(&bar[XB_TOP], 1u);
;             const unsigned tg = og / nx;
;             if (og + 1u == (tg + 1u) * nx) xb_add(&bar[XB_TOPGEN], 1u);
;             else XB_SPIN(xb_ld(&bar[XB_TOPGEN]) == tg, bar);
;             __builtin_amdgcn_fence(__ATOMIC_ACQUIRE, "agent");
;             xb_add(&bar[XB_XGEN(b.x)], 1u);
;             asm volatile("s_waitcnt vmcnt(0)" ::: "memory");
;         } else {
;             XB_SPIN(xb_ld(&bar[XB_XGEN(b.x)]) == gen, bar);
.LBB0_177:
	s_or_b64 exec, exec, s[2:3]
	v_cvt_f32_u32_e32 v4, v2
	s_waitcnt vmcnt(0)
	v_readfirstlane_b32 s2, v3
	v_sub_u32_e32 v3, 0, v2
	v_rcp_iflag_f32_e32 v4, v4
	v_add_u32_e32 v5, s2, v1
	v_mul_f32_e32 v4, 0x4f7ffffe, v4
	v_cvt_u32_f32_e32 v4, v4
	v_mul_lo_u32 v1, v3, v4
	v_mul_hi_u32 v1, v4, v1
	v_add_u32_e32 v1, v4, v1
	v_mul_hi_u32 v1, v5, v1
	v_mul_lo_u32 v3, v1, v2
	v_sub_u32_e32 v3, v5, v3
	v_add_u32_e32 v4, 1, v1
	v_cmp_ge_u32_e32 vcc, v3, v2
	s_nop 1
	v_cndmask_b32_e32 v1, v1, v4, vcc
	v_sub_u32_e32 v4, v3, v2
	v_cndmask_b32_e32 v3, v3, v4, vcc
	v_add_u32_e32 v4, 1, v1
	v_cmp_ge_u32_e32 vcc, v3, v2
	v_add_u32_e32 v3, 1, v5
	s_nop 0
	v_cndmask_b32_e32 v1, v1, v4, vcc
	v_mul_lo_u32 v4, v2, v1
	v_add_u32_e32 v2, v4, v2
	v_cmp_ne_u32_e32 vcc, v3, v2
	s_and_saveexec_b64 s[2:3], vcc
	s_xor_b64 s[2:3], exec, s[2:3]
	s_cbranch_execz .LBB0_191
	v_readlane_b32 s10, v254, 8
	v_readlane_b32 s11, v254, 9
	s_waitcnt lgkmcnt(0)
	s_nop 3
	global_load_dword v0, v36, s[10:11] sc1
	s_waitcnt vmcnt(0)
	v_cmp_eq_u32_e32 vcc, v0, v1
	s_and_saveexec_b64 s[10:11], vcc
	s_cbranch_execz .LBB0_190
	s_mov_b32 s30, s24
	s_mov_b32 s28, s18
	s_mov_b32 s13, 1
	s_mov_b64 s[14:15], 0
	s_branch .LBB0_181

; __device__ __forceinline__ unsigned xb_ld(unsigned* p)              { return __hip_atomic_load(p, __ATOMIC_RELAXED, __HIP_MEMORY_SCOPE_AGENT); }
; #define XB_SPIN(cond, bar) do { unsigned _sp = 0; while (cond) { __builtin_amdgcn_s_sleep(1); \
;     if ((++_sp & 255u) == 0u) { if (xb_ld(&(bar)[XB_TMO])) break; if (_sp > XB_SPIN_CAP) { atomicAdd(&(bar)[XB_TMO], 1u); break; } } } } while (0)
; __device__ __forceinline__ void xcd_barrier(const XcdBarrier& b) {
;     ...
;             XB_SPIN(xb_ld(&bar[XB_XGEN(b.x)]) == gen, bar);
.LBB0_185:
	v_readlane_b32 s18, v254, 8
	v_readlane_b32 s19, v254, 9
	s_add_i32 s13, s13, 1
	s_mov_b64 s[24:25], -1
	s_nop 2
	global_load_dword v0, v36, s[18:19] sc1
	s_waitcnt vmcnt(0)
	v_cmp_ne_u32_e32 vcc, v0, v1
	s_orn2_b64 s[18:19], vcc, exec
	s_branch .LBB0_180

; __device__ __forceinline__ unsigned xb_ld(unsigned* p)              { return __hip_atomic_load(p, __ATOMIC_RELAXED, __HIP_MEMORY_SCOPE_AGENT); }
; __device__ __forceinline__ unsigned xb_add(unsigned* p, unsigned v) { return __hip_atomic_fetch_add(p, v, __ATOMIC_RELAXED, __HIP_MEMORY_SCOPE_AGENT); }
; #define XB_SPIN(cond, bar) do { unsigned _sp = 0; while (cond) { __builtin_amdgcn_s_sleep(1); \
;     if ((++_sp & 255u) == 0u) { if (xb_ld(&(bar)[XB_TMO])) break; if (_sp > XB_SPIN_CAP) { atomicAdd(&(bar)[XB_TMO], 1u); break; } } } } while (0)
; __device__ __forceinline__ void xcd_barrier(const XcdBarrier& b) {
;     ...
;         const unsigned old = xb_add(&bar[XB_XSUB(b.x)], 1u);
;         const unsigned gen = old / nloc;
;         if (old + 1u == (gen + 1u) * nloc) {
;             __builtin_amdgcn_fence(__ATOMIC_RELEASE, "agent");
;             asm volatile("s_waitcnt vmcnt(0)" ::: "memory");
;             const unsigned og = xb_add(&bar[XB_TOP], 1u);
;             const unsigned tg = og / nx;
;             if (og + 1u == (tg + 1u) * nx) xb_add(&bar[XB_TOPGEN], 1u);
;             else XB_SPIN(xb_ld(&bar[XB_TOPGEN]) == tg, bar);
;             __builtin_amdgcn_fence(__ATOMIC_ACQUIRE, "agent");
;             xb_add(&bar[XB_XGEN(b.x)], 1u);
;             asm volatile("s_waitcnt vmcnt(0)" ::: "memory");
;         } else {
;             XB_SPIN(xb_ld(&bar[XB_XGEN(b.x)]) == gen, bar);
.LBB0_2260:
	s_or_b64 exec, exec, s[2:3]
	v_cvt_f32_u32_e32 v4, v2
	s_waitcnt vmcnt(0)
	v_readfirstlane_b32 s2, v3
	v_sub_u32_e32 v3, 0, v2
	v_rcp_iflag_f32_e32 v4, v4
	v_add_u32_e32 v5, s2, v1
	v_mul_f32_e32 v4, 0x4f7ffffe, v4
	v_cvt_u32_f32_e32 v4, v4
	v_mul_lo_u32 v1, v3, v4
	v_mul_hi_u32 v1, v4, v1
	v_add_u32_e32 v1, v4, v1
	v_mul_hi_u32 v1, v5, v1
	v_mul_lo_u32 v3, v1, v2
	v_sub_u32_e32 v3, v5, v3
	v_add_u32_e32 v4, 1, v1
	v_cmp_ge_u32_e32 vcc, v3, v2
	s_nop 1
	v_cndmask_b32_e32 v1, v1, v4, vcc
	v_sub_u32_e32 v4, v3, v2
	v_cndmask_b32_e32 v3, v3, v4, vcc
	v_add_u32_e32 v4, 1, v1
	v_cmp_ge_u32_e32 vcc, v3, v2
	v_add_u32_e32 v3, 1, v5
	s_nop 0
	v_cndmask_b32_e32 v1, v1, v4, vcc
	v_mul_lo_u32 v4, v2, v1
	v_add_u32_e32 v2, v4, v2
	v_cmp_ne_u32_e32 vcc, v3, v2
	s_and_saveexec_b64 s[2:3], vcc
	s_xor_b64 s[2:3], exec, s[2:3]
	s_cbranch_execz .LBB0_2274
	v_readlane_b32 s4, v254, 8
	v_readlane_b32 s5, v254, 9
	s_waitcnt lgkmcnt(0)
	s_nop 3
	global_load_dword v0, v36, s[4:5] sc1
	s_waitcnt vmcnt(0)
	v_cmp_eq_u32_e32 vcc, v0, v1
	s_and_saveexec_b64 s[4:5], vcc
	s_cbranch_execz .LBB0_2273
	s_mov_b32 s13, 1
	s_mov_b64 s[6:7], 0
	s_branch .LBB0_2264

; __device__ __forceinline__ unsigned xb_ld(unsigned* p)              { return __hip_atomic_load(p, __ATOMIC_RELAXED, __HIP_MEMORY_SCOPE_AGENT); }
; #define XB_SPIN(cond, bar) do { unsigned _sp = 0; while (cond) { __builtin_amdgcn_s_sleep(1); \
;     if ((++_sp & 255u) == 0u) { if (xb_ld(&(bar)[XB_TMO])) break; if (_sp > XB_SPIN_CAP) { atomicAdd(&(bar)[XB_TMO], 1u); break; } } } } while (0)
; __device__ __forceinline__ void xcd_barrier(const XcdBarrier& b) {
;     ...
;             XB_SPIN(xb_ld(&bar[XB_XGEN(b.x)]) == gen, bar);
.LBB0_2268:
	v_readlane_b32 s14, v254, 8
	v_readlane_b32 s15, v254, 9
	s_add_i32 s13, s13, 1
	s_mov_b64 s[16:17], -1
	s_nop 2
	global_load_dword v0, v36, s[14:15] sc1
	s_waitcnt vmcnt(0)
	v_cmp_ne_u32_e32 vcc, v0, v1
	s_orn2_b64 s[14:15], vcc, exec
	s_branch .LBB0_2263
